# gate/up GEMM: tile order changed to column-group-major with XCD-chunk permutation (each XCD step = 8x4 tile sub-grid)
# baseline (speedup 1.0000x reference)
.LBB0_151:
	s_and_b32 s98, s0, 7
	s_lshl_b32 s98, s98, 5
	s_bfe_u32 s99, s0, 0x50003
	s_or_b32 s98, s98, s99
	s_andn2_b32 s99, s0, 0xff
	s_or_b32 s98, s98, s99
	s_cmpk_lt_i32 s0, 0x700
	s_cselect_b32 s98, s98, s0
	s_lshr_b32 s99, s98, 5
	s_mulk_i32 s99, 0x175
	s_lshr_b32 s99, s99, 12
	s_mul_i32 s2, s99, 0x160
	s_sub_i32 s2, s98, s2
	s_lshl_b32 s98, s99, 2
	s_cmp_eq_u32 s99, 5
	s_cselect_b32 s1, 1, 2
	s_cselect_b32 s99, 1, 3
	s_and_b32 s99, s2, s99
	s_lshr_b32 s2, s2, s1
	s_add_i32 s1, s98, s99
	s_waitcnt vmcnt(2)
	v_mov_b32_e32 v160, v208
	s_lshl_b32 s1, s1, 8
	v_readlane_b32 s4, v253, 30
	v_ashrrev_i32_e32 v4, 2, v160
	v_add_u32_e32 v0, s1, v4
	v_ashrrev_i32_e32 v1, 31, v0
	v_lshlrev_b64 v[0:1], 11, v[0:1]
	v_readlane_b32 s5, v253, 31
	v_lshlrev_b32_e32 v5, 4, v160
	s_mulk_i32 s2, 0xc0
	v_lshl_add_u64 v[0:1], s[4:5], 0, v[0:1]
	v_and_b32_e32 v192, 48, v5
	v_lshl_add_u64 v[96:97], v[0:1], 0, v[192:193]
	v_add_u32_e32 v0, s2, v4
	v_ashrrev_i32_e32 v1, 31, v0
	v_readlane_b32 s4, v253, 16
	s_mov_b32 s3, 0x20000
	v_lshlrev_b64 v[0:1], 11, v[0:1]
	v_readlane_b32 s5, v253, 17
	v_add_co_u32_e32 v2, vcc, s3, v96
	s_nop 0
	v_lshl_add_u64 v[0:1], s[4:5], 0, v[0:1]
	v_addc_co_u32_e32 v3, vcc, 0, v97, vcc
	s_mov_b32 s4, 0x40000
	v_add_co_u32_e32 v24, vcc, s4, v96
	v_lshl_add_u64 v[98:99], v[0:1], 0, v[192:193]
	s_nop 0
	v_addc_co_u32_e32 v25, vcc, 0, v97, vcc
	v_add_co_u32_e32 v28, vcc, s75, v96
	v_bfe_u32 v1, v160, 5, 1
	s_nop 0
	v_addc_co_u32_e32 v29, vcc, 0, v97, vcc
	v_lshrrev_b32_e32 v6, 2, v160
	v_bfe_u32 v7, v160, 2, 2
	v_lshlrev_b32_e32 v10, 1, v160
	global_load_dwordx4 v[32:35], v[96:97], off
	global_load_dwordx4 v[36:39], v[2:3], off
	global_load_dwordx4 v[40:43], v[24:25], off
	global_load_dwordx4 v[44:47], v[28:29], off
	global_load_dwordx4 v[48:51], v[98:99], off
	v_add_co_u32_e32 v8, vcc, s3, v98
	v_and_b32_e32 v161, 31, v160
	s_waitcnt vmcnt(6)
	v_and_b32_e32 v162, 0x80, v10
	v_bitop3_b32 v6, v1, v6, 3 bitop3:0x78
	v_bitop3_b32 v1, v1, v7, 2 bitop3:0x36
	v_and_b32_e32 v7, 0xffffffe0, v4
	v_addc_co_u32_e32 v9, vcc, 0, v99, vcc
	v_bitop3_b32 v5, v5, 48, v160 bitop3:0x48
	v_or_b32_e32 v10, v162, v161
	v_lshl_add_u32 v163, v7, 1, v7
	v_add_co_u32_e32 v12, vcc, s4, v98
	v_lshlrev_b32_e32 v6, 4, v6
	v_lshlrev_b32_e32 v1, 4, v1
	v_lshl_or_b32 v110, v4, 6, v5
	v_lshlrev_b32_e32 v4, 6, v10
	v_or_b32_e32 v5, v163, v161
	v_addc_co_u32_e32 v13, vcc, 0, v99, vcc
	v_or_b32_e32 v111, v4, v6
	v_or_b32_e32 v116, v4, v1
	v_lshl_add_u32 v4, v5, 6, v214
	global_load_dwordx4 v[52:55], v[8:9], off
	global_load_dwordx4 v[56:59], v[12:13], off
	v_or_b32_e32 v117, v4, v6
	v_or_b32_e32 v118, v4, v1
	global_load_dwordx4 v[4:7], v[98:99], off offset:64
	s_nop 0
	global_load_dwordx4 v[8:11], v[8:9], off offset:64
	s_nop 0
	global_load_dwordx4 v[12:15], v[12:13], off offset:64
	s_nop 0
	global_load_dwordx4 v[16:19], v[96:97], off offset:64
	global_load_dwordx4 v[20:23], v[2:3], off offset:64
	s_nop 0
	global_load_dwordx4 v[24:27], v[24:25], off offset:64
	s_nop 0
	global_load_dwordx4 v[28:31], v[28:29], off offset:64
	s_waitcnt vmcnt(13)
	ds_write_b128 v110, v[32:35] offset:0
	s_waitcnt vmcnt(12)
	ds_write_b128 v110, v[36:39] offset:0x1000
	s_waitcnt vmcnt(11)
	ds_write_b128 v110, v[40:43] offset:0x2000
	s_mov_b64 s[4:5], 0x40000
	v_mov_b32_e32 v0, 0
	s_mov_b64 s[6:7], 0x20000
	v_lshl_add_u64 v[102:103], v[98:99], 0, s[4:5]
	v_lshl_add_u64 v[106:107], v[96:97], 0, s[4:5]
	s_mov_b64 s[4:5], 0x60000
	v_accvgpr_mov_b32 a193, a192
	v_accvgpr_mov_b32 a194, a192
	v_accvgpr_mov_b32 a195, a192
	v_accvgpr_mov_b32 a196, a192
	v_accvgpr_mov_b32 a197, a192
	v_accvgpr_mov_b32 a198, a192
	v_accvgpr_mov_b32 a199, a192
	v_accvgpr_mov_b32 a200, a192
	v_accvgpr_mov_b32 a201, a192
	s_waitcnt vmcnt(10)
	ds_write_b128 v110, v[44:47] offset:0x3000
	s_waitcnt vmcnt(9)
	ds_write_b128 v110, v[48:51] offset:0x4000
	s_waitcnt vmcnt(8)
	ds_write_b128 v110, v[52:55] offset:0x5000
	s_waitcnt vmcnt(7)
	ds_write_b128 v110, v[56:59] offset:0x6000
	s_waitcnt lgkmcnt(0)
	v_accvgpr_mov_b32 a202, a192
	v_accvgpr_mov_b32 a203, a192
	v_accvgpr_mov_b32 a204, a192
	v_accvgpr_mov_b32 a205, a192
	v_accvgpr_mov_b32 a206, a192
	v_accvgpr_mov_b32 a207, a192
	v_accvgpr_mov_b32 a0, a192
	v_accvgpr_mov_b32 a16, a192
	v_accvgpr_mov_b32 a32, a192
	s_mov_b32 s3, 0
	v_accvgpr_write_b32 a95, 0
	v_lshl_add_u64 v[100:101], v[98:99], 0, s[6:7]
	v_lshl_add_u64 v[104:105], v[96:97], 0, s[6:7]
	v_lshl_add_u64 v[108:109], v[96:97], 0, s[4:5]
	v_accvgpr_write_b32 a94, 0
	v_accvgpr_write_b32 a93, 0
	v_accvgpr_write_b32 a92, 0
	v_accvgpr_write_b32 a91, 0
	v_accvgpr_write_b32 a90, 0
	v_accvgpr_write_b32 a89, 0
	v_accvgpr_write_b32 a88, 0
	v_accvgpr_write_b32 a87, 0
	v_accvgpr_write_b32 a86, 0
	v_accvgpr_write_b32 a85, 0
	v_accvgpr_write_b32 a84, 0
	v_accvgpr_write_b32 a83, 0
	v_accvgpr_write_b32 a82, 0
	v_accvgpr_write_b32 a81, 0
	v_accvgpr_write_b32 a80, 0
	v_accvgpr_write_b32 a63, 0
	v_accvgpr_write_b32 a62, 0
	v_accvgpr_write_b32 a61, 0
	v_accvgpr_write_b32 a60, 0
	v_accvgpr_write_b32 a59, 0
	v_accvgpr_write_b32 a58, 0
	v_accvgpr_write_b32 a57, 0
	v_accvgpr_write_b32 a56, 0
	v_accvgpr_write_b32 a55, 0
	v_accvgpr_write_b32 a54, 0
	v_accvgpr_write_b32 a53, 0
	v_accvgpr_write_b32 a52, 0
	v_accvgpr_write_b32 a51, 0
	v_accvgpr_write_b32 a50, 0
	v_accvgpr_write_b32 a49, 0
	v_accvgpr_write_b32 a48, 0
	v_accvgpr_write_b32 a79, 0
	v_accvgpr_write_b32 a78, 0
	v_accvgpr_write_b32 a77, 0
	v_accvgpr_write_b32 a76, 0
	v_accvgpr_write_b32 a75, 0
	v_accvgpr_write_b32 a74, 0
	v_accvgpr_write_b32 a73, 0
	v_accvgpr_write_b32 a72, 0
	v_accvgpr_write_b32 a71, 0
	v_accvgpr_write_b32 a70, 0
	v_accvgpr_write_b32 a69, 0
	v_accvgpr_write_b32 a68, 0
	v_accvgpr_write_b32 a67, 0
	v_accvgpr_write_b32 a66, 0
	v_accvgpr_write_b32 a65, 0
	v_accvgpr_write_b32 a64, 0
	v_accvgpr_write_b32 a111, 0
	v_accvgpr_write_b32 a110, 0
	v_accvgpr_write_b32 a109, 0
	v_accvgpr_write_b32 a108, 0
	v_accvgpr_write_b32 a107, 0
	v_accvgpr_write_b32 a106, 0
	v_accvgpr_write_b32 a105, 0
	v_accvgpr_write_b32 a104, 0
	v_accvgpr_write_b32 a103, 0
	v_accvgpr_write_b32 a102, 0
	v_accvgpr_write_b32 a101, 0
	v_accvgpr_write_b32 a100, 0
	v_accvgpr_write_b32 a99, 0
	v_accvgpr_write_b32 a98, 0
	v_accvgpr_write_b32 a97, 0
	v_accvgpr_write_b32 a96, 0
	v_accvgpr_write_b32 a127, 0
	v_accvgpr_write_b32 a126, 0
	v_accvgpr_write_b32 a125, 0
	v_accvgpr_write_b32 a124, 0
	v_accvgpr_write_b32 a123, 0
	v_accvgpr_write_b32 a122, 0
	v_accvgpr_write_b32 a121, 0
	v_accvgpr_write_b32 a120, 0
	v_accvgpr_write_b32 a119, 0
	v_accvgpr_write_b32 a118, 0
	v_accvgpr_write_b32 a117, 0
	v_accvgpr_write_b32 a116, 0
	v_accvgpr_write_b32 a115, 0
	v_accvgpr_write_b32 a114, 0
	v_accvgpr_write_b32 a113, 0
	v_accvgpr_write_b32 a112, 0
	v_accvgpr_write_b32 a143, 0
	v_accvgpr_write_b32 a142, 0
	v_accvgpr_write_b32 a141, 0
	v_accvgpr_write_b32 a140, 0
	v_accvgpr_write_b32 a139, 0
	v_accvgpr_write_b32 a138, 0
	v_accvgpr_write_b32 a137, 0
	v_accvgpr_write_b32 a136, 0
	v_accvgpr_write_b32 a135, 0
	v_accvgpr_write_b32 a134, 0
	v_accvgpr_write_b32 a133, 0
	v_accvgpr_write_b32 a132, 0
	v_accvgpr_write_b32 a131, 0
	v_accvgpr_write_b32 a130, 0
	v_accvgpr_write_b32 a129, 0
	v_accvgpr_write_b32 a128, 0
	v_accvgpr_write_b32 a159, 0
	v_accvgpr_write_b32 a158, 0
	v_accvgpr_write_b32 a157, 0
	v_accvgpr_write_b32 a156, 0
	v_accvgpr_write_b32 a155, 0
	v_accvgpr_write_b32 a154, 0
	v_accvgpr_write_b32 a153, 0
	v_accvgpr_write_b32 a152, 0
	v_accvgpr_write_b32 a151, 0
	v_accvgpr_write_b32 a150, 0
	v_accvgpr_write_b32 a149, 0
	v_accvgpr_write_b32 a148, 0
	v_accvgpr_write_b32 a147, 0
	v_accvgpr_write_b32 a146, 0
	v_accvgpr_write_b32 a145, 0
	v_accvgpr_write_b32 a144, 0
	v_accvgpr_write_b32 a175, 0
	v_accvgpr_write_b32 a174, 0
	v_accvgpr_write_b32 a173, 0
	v_accvgpr_write_b32 a172, 0
	v_accvgpr_write_b32 a171, 0
	v_accvgpr_write_b32 a170, 0
	v_accvgpr_write_b32 a169, 0
	v_accvgpr_write_b32 a168, 0
	v_accvgpr_write_b32 a167, 0
	v_accvgpr_write_b32 a166, 0
	v_accvgpr_write_b32 a165, 0
	v_accvgpr_write_b32 a164, 0
	v_accvgpr_write_b32 a163, 0
	v_accvgpr_write_b32 a162, 0
	v_accvgpr_write_b32 a161, 0
	v_accvgpr_write_b32 a160, 0
	v_accvgpr_write_b32 a191, 0
	v_accvgpr_write_b32 a190, 0
	v_accvgpr_write_b32 a189, 0
	v_accvgpr_write_b32 a188, 0
	v_accvgpr_write_b32 a187, 0
	v_accvgpr_write_b32 a186, 0
	v_accvgpr_write_b32 a185, 0
	v_accvgpr_write_b32 a184, 0
	v_accvgpr_write_b32 a183, 0
	v_accvgpr_write_b32 a182, 0
	v_accvgpr_write_b32 a181, 0
	v_accvgpr_write_b32 a180, 0
	v_accvgpr_write_b32 a179, 0
	v_accvgpr_write_b32 a178, 0
	v_accvgpr_write_b32 a177, 0
	v_accvgpr_write_b32 a176, 0
	s_mov_b32 s4, -2
	v_accvgpr_mov_b32 a1, a193
	v_accvgpr_mov_b32 a2, a194
	v_accvgpr_mov_b32 a3, a195
	v_accvgpr_mov_b32 a4, a196
	v_accvgpr_mov_b32 a5, a197
	v_accvgpr_mov_b32 a6, a198
	v_accvgpr_mov_b32 a7, a199
	v_accvgpr_mov_b32 a8, a200
	v_accvgpr_mov_b32 a9, a201
	v_accvgpr_mov_b32 a10, a202
	v_accvgpr_mov_b32 a11, a203
	v_accvgpr_mov_b32 a12, a204
	v_accvgpr_mov_b32 a13, a205
	v_accvgpr_mov_b32 a14, a206
	v_accvgpr_mov_b32 a15, a207
	v_accvgpr_mov_b32 a17, a193
	v_accvgpr_mov_b32 a18, a194
	v_accvgpr_mov_b32 a19, a195
	v_accvgpr_mov_b32 a20, a196
	v_accvgpr_mov_b32 a21, a197
	v_accvgpr_mov_b32 a22, a198
	v_accvgpr_mov_b32 a23, a199
	v_accvgpr_mov_b32 a24, a200
	v_accvgpr_mov_b32 a25, a201
	v_accvgpr_mov_b32 a26, a202
	v_accvgpr_mov_b32 a27, a203
	v_accvgpr_mov_b32 a28, a204
	v_accvgpr_mov_b32 a29, a205
	v_accvgpr_mov_b32 a30, a206
	v_accvgpr_mov_b32 a31, a207
	v_accvgpr_mov_b32 a33, a193
	v_accvgpr_mov_b32 a34, a194
	v_accvgpr_mov_b32 a35, a195
	v_accvgpr_mov_b32 a36, a196
	v_accvgpr_mov_b32 a37, a197
	v_accvgpr_mov_b32 a38, a198
	v_accvgpr_mov_b32 a39, a199
	v_accvgpr_mov_b32 a40, a200
	v_accvgpr_mov_b32 a41, a201
	v_accvgpr_mov_b32 a42, a202
	v_accvgpr_mov_b32 a43, a203
	v_accvgpr_mov_b32 a44, a204
	v_accvgpr_mov_b32 a45, a205
	v_accvgpr_mov_b32 a46, a206
	v_accvgpr_mov_b32 a47, a207
	v_mov_b32_e32 v1, v0
	v_mov_b32_e32 v2, v0
	v_mov_b32_e32 v3, v0
	v_mov_b32_e32 v128, v0
	v_mov_b32_e32 v129, v0
	v_mov_b32_e32 v130, v0
	v_mov_b32_e32 v131, v0
	v_mov_b32_e32 v32, v0
	v_mov_b32_e32 v33, v0
	v_mov_b32_e32 v34, v0
	v_mov_b32_e32 v35, v0
	s_barrier
